# P2 cumsum unit: the eight 16-B loads of each inner iteration issued together (were one load, one full wait each: 32 dependent round trips on the two workgroups that also run two SSD units)
# baseline (speedup 1.0000x reference)
.LBB0_1112:
	v_lshl_add_u64 v[2:3], v[6:7], 0, s[14:15]
	global_load_dwordx4 v[112:115], v[2:3], off
	v_lshl_add_u64 v[6:7], v[6:7], 0, s[66:67]
	v_lshl_add_u64 v[2:3], v[8:9], 0, s[14:15]
	global_load_dwordx4 v[116:119], v[2:3], off
	v_lshl_add_u64 v[8:9], v[8:9], 0, s[66:67]
	v_lshl_add_u64 v[2:3], v[10:11], 0, s[14:15]
	global_load_dwordx4 v[120:123], v[2:3], off
	v_lshl_add_u64 v[10:11], v[10:11], 0, s[66:67]
	v_lshl_add_u64 v[2:3], v[22:23], 0, s[14:15]
	global_load_dwordx4 v[124:127], v[2:3], off
	v_lshl_add_u64 v[22:23], v[22:23], 0, s[66:67]
	v_lshl_add_u64 v[2:3], v[20:21], 0, s[14:15]
	global_load_dwordx4 v[128:131], v[2:3], off
	v_lshl_add_u64 v[20:21], v[20:21], 0, s[66:67]
	v_lshl_add_u64 v[2:3], v[18:19], 0, s[14:15]
	global_load_dwordx4 v[132:135], v[2:3], off
	v_lshl_add_u64 v[18:19], v[18:19], 0, s[66:67]
	v_lshl_add_u64 v[2:3], v[16:17], 0, s[14:15]
	global_load_dwordx4 v[136:139], v[2:3], off
	v_lshl_add_u64 v[16:17], v[16:17], 0, s[66:67]
	v_lshl_add_u64 v[2:3], v[14:15], 0, s[14:15]
	global_load_dwordx4 v[140:143], v[2:3], off
	v_lshl_add_u64 v[14:15], v[14:15], 0, s[66:67]
	s_mov_b32 s5, 0x1986000
	s_add_i32 s4, s4, -1
	s_cmp_eq_u32 s4, 0
	s_waitcnt vmcnt(7)
	ds_write_b32 v26, v112
	ds_write_b32 v26, v113 offset:9232
	ds_write_b32 v26, v114 offset:18464
	ds_write_b32 v26, v115 offset:27696
	s_waitcnt vmcnt(6)
	ds_write_b32 v27, v116
	ds_write_b32 v27, v117 offset:9232
	ds_write_b32 v27, v118 offset:18464
	ds_write_b32 v27, v119 offset:27696
	s_waitcnt vmcnt(5)
	ds_write_b32 v28, v120
	ds_write_b32 v28, v121 offset:9232
	ds_write_b32 v28, v122 offset:18464
	ds_write_b32 v28, v123 offset:27696
	s_waitcnt vmcnt(4)
	ds_write_b32 v29, v124
	ds_write_b32 v29, v125 offset:9232
	ds_write_b32 v29, v126 offset:18464
	ds_write_b32 v29, v127 offset:27696
	s_waitcnt vmcnt(3)
	ds_write_b32 v30, v128
	ds_write_b32 v30, v129 offset:9232
	ds_write_b32 v30, v130 offset:18464
	ds_write_b32 v30, v131 offset:27696
	s_waitcnt vmcnt(2)
	ds_write_b32 v31, v132
	ds_write_b32 v31, v133 offset:9232
	ds_write_b32 v31, v134 offset:18464
	ds_write_b32 v31, v135 offset:27696
	s_waitcnt vmcnt(1)
	ds_write_b32 v32, v136
	ds_write_b32 v32, v137 offset:9232
	ds_write_b32 v32, v138 offset:18464
	ds_write_b32 v32, v139 offset:27696
	s_waitcnt vmcnt(0)
	ds_write_b32 v33, v140
	ds_write_b32 v33, v141 offset:9232
	ds_write_b32 v33, v142 offset:18464
	ds_write_b32 v33, v143 offset:27696
	s_waitcnt lgkmcnt(0)
	s_barrier
	ds_read_b128 v[2:5], v24
	ds_read_b128 v[48:51], v24 offset:16
	ds_read_b128 v[52:55], v24 offset:32
	ds_read_b128 v[56:59], v24 offset:48
	s_waitcnt lgkmcnt(3)
	v_add_f32_e32 v60, 0, v2
	v_add_f32_e32 v61, v3, v60
	v_add_f32_e32 v62, v4, v61
	v_add_f32_e32 v63, v5, v62
	s_waitcnt lgkmcnt(2)
	v_add_f32_e32 v48, v48, v63
	v_add_f32_e32 v49, v49, v48
	v_add_f32_e32 v50, v50, v49
	v_add_f32_e32 v51, v51, v50
	s_waitcnt lgkmcnt(1)
	v_add_f32_e32 v52, v52, v51
	v_add_f32_e32 v53, v53, v52
	v_add_f32_e32 v54, v54, v53
	v_add_f32_e32 v55, v55, v54
	ds_read_b128 v[2:5], v24 offset:64
	s_waitcnt lgkmcnt(1)
	v_add_f32_e32 v56, v56, v55
	v_add_f32_e32 v57, v57, v56
	v_add_f32_e32 v58, v58, v57
	v_add_f32_e32 v59, v59, v58
	s_waitcnt lgkmcnt(0)
	v_add_f32_e32 v64, v2, v59
	v_add_f32_e32 v65, v3, v64
	v_add_f32_e32 v66, v4, v65
	v_add_f32_e32 v67, v5, v66
	ds_read_b128 v[2:5], v24 offset:80
	s_waitcnt lgkmcnt(0)
	v_add_f32_e32 v68, v2, v67
	v_add_f32_e32 v69, v3, v68
	v_add_f32_e32 v70, v4, v69
	v_add_f32_e32 v71, v5, v70
	ds_read_b128 v[2:5], v24 offset:96
	s_waitcnt lgkmcnt(0)
	v_add_f32_e32 v72, v2, v71
	v_add_f32_e32 v73, v3, v72
	v_add_f32_e32 v74, v4, v73
	v_add_f32_e32 v75, v5, v74
	ds_read_b128 v[2:5], v24 offset:112
	s_waitcnt lgkmcnt(0)
	v_add_f32_e32 v76, v2, v75
	v_add_f32_e32 v77, v3, v76
	v_add_f32_e32 v80, v4, v77
	v_add_f32_e32 v81, v5, v80
	ds_bpermute_b32 v2, v34, v81
	s_waitcnt lgkmcnt(0)
	v_add_f32_e32 v2, v81, v2
	v_cndmask_b32_e32 v2, v2, v81, vcc
	ds_bpermute_b32 v3, v35, v2
	s_waitcnt lgkmcnt(0)
	v_add_f32_e32 v3, v2, v3
	v_cndmask_b32_e64 v2, v3, v2, s[0:1]
	ds_bpermute_b32 v3, v36, v2
	s_waitcnt lgkmcnt(0)
	v_add_f32_e32 v3, v2, v3
	v_cndmask_b32_e64 v2, v3, v2, s[2:3]
	ds_bpermute_b32 v3, v37, v2
	s_waitcnt lgkmcnt(0)
	v_add_f32_e32 v3, v2, v3
	v_cndmask_b32_e64 v2, v3, v2, s[6:7]
	ds_bpermute_b32 v3, v38, v2
	s_waitcnt lgkmcnt(0)
	v_add_f32_e32 v3, v2, v3
	v_cndmask_b32_e64 v2, v3, v2, s[8:9]
	ds_bpermute_b32 v3, v39, v2
	s_waitcnt lgkmcnt(0)
	v_add_f32_e32 v3, v2, v3
	v_cndmask_b32_e64 v105, v3, v2, s[10:11]
	v_add_f32_e32 v2, v47, v105
	v_sub_f32_e32 v78, v2, v81
	v_pk_add_f32 v[2:3], v[60:61], v[78:79] op_sel_hi:[1,0]
	v_pk_add_f32 v[4:5], v[62:63], v[78:79] op_sel_hi:[1,0]
	v_pk_mul_f32 v[2:3], v[2:3], s[62:63] op_sel_hi:[1,0]
	v_pk_mul_f32 v[4:5], v[4:5], s[62:63] op_sel_hi:[1,0]
	ds_write_b128 v24, v[2:5]
	v_pk_add_f32 v[2:3], v[48:49], v[78:79] op_sel_hi:[1,0]
	v_pk_add_f32 v[4:5], v[50:51], v[78:79] op_sel_hi:[1,0]
	v_pk_mul_f32 v[2:3], v[2:3], s[62:63] op_sel_hi:[1,0]
	v_pk_mul_f32 v[4:5], v[4:5], s[62:63] op_sel_hi:[1,0]
	ds_write_b128 v24, v[2:5] offset:16
	v_pk_add_f32 v[2:3], v[52:53], v[78:79] op_sel_hi:[1,0]
	v_pk_add_f32 v[4:5], v[54:55], v[78:79] op_sel_hi:[1,0]
	v_pk_mul_f32 v[2:3], v[2:3], s[62:63] op_sel_hi:[1,0]
	v_pk_mul_f32 v[4:5], v[4:5], s[62:63] op_sel_hi:[1,0]
	ds_write_b128 v24, v[2:5] offset:32
	v_pk_add_f32 v[2:3], v[56:57], v[78:79] op_sel_hi:[1,0]
	v_pk_add_f32 v[4:5], v[58:59], v[78:79] op_sel_hi:[1,0]
	v_pk_mul_f32 v[2:3], v[2:3], s[62:63] op_sel_hi:[1,0]
	v_pk_mul_f32 v[4:5], v[4:5], s[62:63] op_sel_hi:[1,0]
	ds_write_b128 v24, v[2:5] offset:48
	v_pk_add_f32 v[2:3], v[64:65], v[78:79] op_sel_hi:[1,0]
	v_pk_add_f32 v[4:5], v[66:67], v[78:79] op_sel_hi:[1,0]
	v_pk_mul_f32 v[2:3], v[2:3], s[62:63] op_sel_hi:[1,0]
	v_pk_mul_f32 v[4:5], v[4:5], s[62:63] op_sel_hi:[1,0]
	ds_write_b128 v24, v[2:5] offset:64
	v_pk_add_f32 v[2:3], v[68:69], v[78:79] op_sel_hi:[1,0]
	v_pk_add_f32 v[4:5], v[70:71], v[78:79] op_sel_hi:[1,0]
	v_pk_mul_f32 v[2:3], v[2:3], s[62:63] op_sel_hi:[1,0]
	v_pk_mul_f32 v[4:5], v[4:5], s[62:63] op_sel_hi:[1,0]
	ds_write_b128 v24, v[2:5] offset:80
	v_pk_add_f32 v[2:3], v[72:73], v[78:79] op_sel_hi:[1,0]
	v_pk_add_f32 v[4:5], v[74:75], v[78:79] op_sel_hi:[1,0]
	v_pk_mul_f32 v[2:3], v[2:3], s[62:63] op_sel_hi:[1,0]
	v_pk_mul_f32 v[4:5], v[4:5], s[62:63] op_sel_hi:[1,0]
	ds_write_b128 v24, v[2:5] offset:96
	v_pk_add_f32 v[2:3], v[76:77], v[78:79] op_sel_hi:[1,0]
	v_pk_add_f32 v[4:5], v[80:81], v[78:79] op_sel_hi:[1,0]
	v_pk_mul_f32 v[2:3], v[2:3], s[62:63] op_sel_hi:[1,0]
	v_pk_mul_f32 v[4:5], v[4:5], s[62:63] op_sel_hi:[1,0]
	ds_write_b128 v24, v[2:5] offset:112
	s_waitcnt lgkmcnt(0)
	s_barrier
	ds_read_b128 v[2:5], v25
	v_lshl_add_u64 v[50:51], v[12:13], 0, s[14:15]
	v_add_co_u32_e64 v52, s[12:13], s5, v50
	s_mov_b32 s5, 0x1987000
	s_nop 0
	v_addc_co_u32_e64 v53, s[12:13], 0, v51, s[12:13]
	s_waitcnt lgkmcnt(0)
	global_store_dwordx4 v[52:53], v[2:5], off offset:512
	ds_read_b128 v[2:5], v40 offset:1024
	v_add_co_u32_e64 v50, s[12:13], s5, v50
	ds_bpermute_b32 v48, v86, v105
	s_nop 0
	v_addc_co_u32_e64 v51, s[12:13], 0, v51, s[12:13]
	s_waitcnt lgkmcnt(1)
	global_store_dwordx4 v[52:53], v[2:5], off offset:1536
	ds_read_b128 v[2:5], v41 offset:2048
	s_mov_b64 s[12:13], 0x2000
	s_waitcnt lgkmcnt(1)
	v_add_f32_e32 v47, v47, v48
	v_lshl_add_u64 v[12:13], v[12:13], 0, s[12:13]
	s_waitcnt lgkmcnt(0)
	global_store_dwordx4 v[52:53], v[2:5], off offset:2560
	ds_read_b128 v[2:5], v42 offset:3072
	s_waitcnt lgkmcnt(0)
	global_store_dwordx4 v[52:53], v[2:5], off offset:3584
	ds_read_b128 v[2:5], v43 offset:4096
	s_waitcnt lgkmcnt(0)
	global_store_dwordx4 v[50:51], v[2:5], off offset:512
	ds_read_b128 v[2:5], v44 offset:5120
	s_waitcnt lgkmcnt(0)
	global_store_dwordx4 v[50:51], v[2:5], off offset:1536
	ds_read_b128 v[2:5], v45 offset:6144
	s_waitcnt lgkmcnt(0)
	global_store_dwordx4 v[50:51], v[2:5], off offset:2560
	ds_read_b128 v[2:5], v46 offset:7168
	s_waitcnt lgkmcnt(0)
	global_store_dwordx4 v[50:51], v[2:5], off offset:3584
	s_barrier
	s_cbranch_scc0 .LBB0_1112
	s_mov_b64 s[0:1], 0
